# NSA selected-block loop: waves 4-7 stage and rendezvous mid-tile (half-iteration stagger vs waves 0-3), plus v24 changes
# baseline (speedup 1.0000x reference)
; DI void nsa_unit(const bf16* PR, const bf16* VT, const bf16* kcb, const bf16* vctb, bf16* Y, LAS unsigned char* lds, int b, int g, int jt) {
;     ...
;         Soft f; soft_init(f);
;         const bf16* ks = PR + ((size_t)(12 + g) * NTOK + (size_t)b * SEQ) * 64; const bf16* vst = VT + ((size_t)(g * 4 + b) * 64) * SEQ;
;         const float ab = slope2 * (float)t;
;         int itw = 3; unsigned itbits = gu3;
;     ...
;         int jcur; SEL_NEXT(jcur);
;         stage_load(R, ks + (size_t)jcur * 64 * 64, 64, vst + 64 * jcur, SEQ, tid, true); stage_store(tb, R, tid, true); __syncthreads();
;         int par = 0;
.LBB0_990:
	v_cvt_f32_i32_e32 v1, v204
	s_andn2_b64 vcc, exec, s[4:5]
	v_lshlrev_b64 v[164:165], 13, v[108:109]
	v_mul_f32_e32 v247, v208, v1
	s_cbranch_vccnz .LBB0_1012
	s_lshl_b32 s2, 1, s2
	s_andn2_b32 s0, s0, s2
	v_readlane_b32 s2, v254, 41
	v_readlane_b32 s3, v254, 42
	v_mov_b32_e32 v171, v0
	v_mov_b32_e32 v14, v0
	v_lshl_add_u64 v[2:3], s[2:3], 0, v[168:169]
	v_readlane_b32 s2, v254, 43
	v_readlane_b32 s3, v254, 44
	v_lshl_add_u64 v[160:161], v[2:3], 0, v[170:171]
	v_mov_b32_e32 v15, v0
	v_lshl_add_u64 v[2:3], v[164:165], 1, s[2:3]
	v_lshl_add_u64 v[162:163], v[2:3], 0, v[170:171]
	v_mov_b32_e32 v1, v0
	v_mov_b32_e32 v2, v0
	v_mov_b32_e32 v3, v0
	v_mov_b32_e32 v4, v0
	v_mov_b32_e32 v5, v0
	v_mov_b32_e32 v6, v0
	v_mov_b32_e32 v7, v0
	v_mov_b32_e32 v8, v0
	v_mov_b32_e32 v9, v0
	v_mov_b32_e32 v10, v0
	v_mov_b32_e32 v11, v0
	v_mov_b32_e32 v12, v0
	v_mov_b32_e32 v13, v0
	v_mov_b64_e32 v[62:63], v[14:15]
	v_mov_b64_e32 v[78:79], v[14:15]
	v_mov_b32_e32 v209, v208
	s_mov_b32 s2, 0
	v_readfirstlane_b32 s54, v188
	s_lshr_b32 s54, s54, 8
	s_mov_b32 s55, 0
	v_mov_b32_e32 v211, 0
	s_mov_b64 s[4:5], 0
	v_mov_b32_e32 v167, 0
	v_mov_b64_e32 v[60:61], v[12:13]
	v_mov_b64_e32 v[58:59], v[10:11]
	v_mov_b64_e32 v[56:57], v[8:9]
	v_mov_b64_e32 v[54:55], v[6:7]
	v_mov_b64_e32 v[52:53], v[4:5]
	v_mov_b64_e32 v[50:51], v[2:3]
	v_mov_b64_e32 v[48:49], v[0:1]
	v_mov_b64_e32 v[76:77], v[12:13]
	v_mov_b64_e32 v[74:75], v[10:11]
	v_mov_b64_e32 v[72:73], v[8:9]
	v_mov_b64_e32 v[70:71], v[6:7]
	v_mov_b64_e32 v[68:69], v[4:5]
	v_mov_b64_e32 v[66:67], v[2:3]
	v_mov_b64_e32 v[64:65], v[0:1]

; #define LAS __attribute__((address_space(3)))
; DI void stage_store(LAS unsigned char* buf, const StageRegs& R, int tid, bool withV) {
;     const int rw = tid >> 3, ch = tid & 7;
;     *(LAS u32x4*)(buf + rw * 144 + ch * 16) = R.k;
;     if (withV) { LAS u32x2* p = (LAS u32x2*)(buf + KB_BYTES + rw * 136 + ch * 16); u32x2 a, b2; a.x = R.v.x; a.y = R.v.y; b2.x = R.v.z; b2.y = R.v.w; p[0] = a; p[1] = b2; }
; }
; DI void nsa_unit(const bf16* PR, const bf16* VT, const bf16* kcb, const bf16* vctb, bf16* Y, LAS unsigned char* lds, int b, int g, int jt) {
;     ...
;             if (jnext >= 0) stage_store(tb + (par ^ 1) * TBUF, R, tid, true);
;             __syncthreads();
.LBB0_1001:
	s_cmp_eq_u32 s54, 0
	s_cbranch_scc1 .Lsel_mid_done
	s_andn2_b64 vcc, exec, s[42:43]
	s_cbranch_vccnz .Lsel_mid_bar
	s_xor_b32 s56, s2, 1
	s_mul_i32 s56, s56, 0x4600
	s_movk_i32 s57, 0x2400
	v_add_u32_e32 v179, s56, v243
	v_add3_u32 v178, s56, v241, v242
	v_add3_u32 v179, v179, v242, s57
	s_waitcnt vmcnt(1)
	ds_write_b128 v178, v[116:119]
	s_waitcnt vmcnt(0)
	ds_write2_b64 v179, v[120:121], v[122:123] offset1:1
.Lsel_mid_bar:
	s_waitcnt lgkmcnt(0)
	s_barrier
	s_mov_b32 s55, 1

; DI void nsa_unit(const bf16* PR, const bf16* VT, const bf16* kcb, const bf16* vctb, bf16* Y, LAS unsigned char* lds, int b, int g, int jt) {
;     ...
;             if (jnext >= 0) stage_store(tb + (par ^ 1) * TBUF, R, tid, true);
;             __syncthreads();
;             par ^= 1; jcur = jnext;
.LBB0_1008:
	s_andn2_b64 vcc, exec, s[42:43]
	s_xor_b32 s2, s2, 1
	s_cmp_eq_u32 s55, 1
	s_cbranch_scc1 .Lsel_end_skip
	s_cbranch_vccnz .LBB0_1010
	s_mul_i32 s6, s2, 0x4600
	s_add_i32 s6, s6, 0
	v_add_u32_e32 v1, s6, v243
	s_movk_i32 s7, 0x2400
	v_add3_u32 v2, s6, v241, v242
	v_add3_u32 v1, v1, v242, s7
	s_waitcnt vmcnt(1)
	ds_write_b128 v2, v[116:119]
	s_waitcnt vmcnt(0)
	ds_write2_b64 v1, v[120:121], v[122:123] offset1:1

; DI void nsa_unit(const bf16* PR, const bf16* VT, const bf16* kcb, const bf16* vctb, bf16* Y, LAS unsigned char* lds, int b, int g, int jt) {
;     ...
;         int jcur; SEL_NEXT(jcur);
;         stage_load(R, ks + (size_t)jcur * 64 * 64, 64, vst + 64 * jcur, SEQ, tid, true); stage_store(tb, R, tid, true); __syncthreads();
;         int par = 0;
;         while (jcur >= 0) {
;             int jnext; SEL_NEXT(jnext);
;     ...
;             par ^= 1; jcur = jnext;
.Lsel_end_skip:
	s_mov_b32 s55, 0
	s_lshl_b32 s6, 1, s53
	s_andn2_b32 s0, s0, s6
	s_andn2_b64 vcc, exec, s[40:41]
	s_cbranch_vccz .LBB0_1013
	s_mov_b32 s10, s3
	s_branch .LBB0_992
